# HGRN: mid-chunk prefetch register moves (and their vmcnt(2)) moved to the chunk end, stacked on v81
# baseline (speedup 1.0000x reference)
; __device__ __forceinline__ void hgrn_phase(const Args& A, unsigned char* smem, const bool dry) {
;     ...
;             f32x4 yst[4];
;             {
;                 bf16x8 aq[4], kf[2][4];
; #pragma unroll
;                 for (int ks = 0; ks < 4; ++ks) aq[ks] = *(const bf16x8*)(Qt + (16 * it + r16) * 136 + 32 * ks + 8 * q4);
; #pragma unroll
;                 for (int jj = 0; jj < 2; ++jj)
; #pragma unroll
;                     for (int ks = 0; ks < 4; ++ks) kf[jj][ks] = *(const bf16x8*)(Kt + (16 * (2 * hh + jj) + r16) * 136 + 32 * ks + 8 * q4);
;                 __builtin_amdgcn_sched_barrier(0);
;                 f32x4 gacc[2];
; #pragma unroll
;                 for (int jj = 0; jj < 2; ++jj) { gacc[jj] = (f32x4){0.f, 0.f, 0.f, 0.f};
; #pragma unroll
;                     for (int ks = 0; ks < 4; ++ks) gacc[jj] = __builtin_amdgcn_mfma_f32_16x16x32_bf16(kf[jj][ks], aq[ks], gacc[jj], 0, 0, 0); }
; #pragma unroll
;                 for (int half = 0; half < 2; ++half) {
;                     bf16x8 sf[2][4];
; #pragma unroll
;                     for (int v2 = 0; v2 < 2; ++v2)
; #pragma unroll
;                         for (int ks = 0; ks < 4; ++ks) sf[v2][ks] = *(const bf16x8*)(Sb + (16 * (4 * hh + 2 * half + v2) + r16) * 136 + 32 * ks + 8 * q4);
;                     __builtin_amdgcn_sched_barrier(0);
; #pragma unroll
;                     for (int v2 = 0; v2 < 2; ++v2) { f32x4 acc = (f32x4){0.f, 0.f, 0.f, 0.f};
; #pragma unroll
;                         for (int ks = 0; ks < 4; ++ks) acc = __builtin_amdgcn_mfma_f32_16x16x32_bf16(aq[ks], sf[v2][ks], acc, 0, 0, 0);
;                         yst[2 * half + v2] = acc; } }
;                 const int i = 16 * it + r16;
; #pragma unroll
;                 for (int jj = 0; jj < 2; ++jj) { const int jt = 2 * hh + jj; float m[4];
; #pragma unroll
;                     for (int r = 0; r < 4; ++r) { const int j = 16 * jt + 4 * q4 + r; m[r] = (j <= i) ? gacc[jj][r] : 0.f; }
;                     u32x2 outw; outw.x = pk2(m[0], m[1]); outw.y = pk2(m[2], m[3]);
;                     *(u32x2*)(Ab + (16 * it + r16) * 72 + 16 * jt + 4 * q4) = outw; }
;             }
;             __syncthreads();
;             {
;                 bf16x8 aa[2], af[2], vf[8][2];
; #pragma unroll
.LBB0_984:
	s_waitcnt lgkmcnt(0)
	s_barrier
	ds_read_b128 v[32:35], v139
	ds_read_b128 v[36:39], v139 offset:64
	ds_read_b128 v[48:51], v139 offset:128
	ds_read_b128 v[154:157], v139 offset:192
	ds_read_b128 v[52:55], v140 offset:17408
	ds_read_b128 v[56:59], v140 offset:17472
	ds_read_b128 v[60:63], v140 offset:17536
	ds_read_b128 v[64:67], v140 offset:17600
	ds_read_b128 v[68:71], v140 offset:21760
	ds_read_b128 v[72:75], v140 offset:21824
	ds_read_b128 v[76:79], v140 offset:21888
	ds_read_b128 v[158:161], v140 offset:21952
	s_waitcnt lgkmcnt(7)
	v_mfma_f32_16x16x32_bf16 v[52:55], v[52:55], v[32:35], 0
	s_waitcnt lgkmcnt(6)
	v_mfma_f32_16x16x32_bf16 v[52:55], v[56:59], v[36:39], v[52:55]
	s_waitcnt lgkmcnt(3)
	v_mfma_f32_16x16x32_bf16 v[56:59], v[68:71], v[32:35], 0
	s_waitcnt lgkmcnt(2)
	v_mfma_f32_16x16x32_bf16 v[56:59], v[72:75], v[36:39], v[56:59]
	v_mfma_f32_16x16x32_bf16 v[52:55], v[60:63], v[48:51], v[52:55]
	s_waitcnt lgkmcnt(1)
	v_mfma_f32_16x16x32_bf16 v[56:59], v[76:79], v[48:51], v[56:59]
	v_mfma_f32_16x16x32_bf16 v[52:55], v[64:67], v[154:157], v[52:55]
	ds_read_b128 v[60:63], v141
	ds_read_b128 v[64:67], v141 offset:64
	ds_read_b128 v[68:71], v141 offset:128
	ds_read_b128 v[72:75], v141 offset:192
	ds_read_b128 v[76:79], v141 offset:4352
	ds_read_b128 v[162:165], v141 offset:4416
	ds_read_b128 v[166:169], v141 offset:4480
	ds_read_b128 v[170:173], v141 offset:4544
	s_waitcnt lgkmcnt(8)
	v_mfma_f32_16x16x32_bf16 v[56:59], v[158:161], v[154:157], v[56:59]
	s_waitcnt lgkmcnt(7)
	v_mfma_f32_16x16x32_bf16 v[60:63], v[32:35], v[60:63], 0
	s_waitcnt lgkmcnt(6)
	v_mfma_f32_16x16x32_bf16 v[60:63], v[36:39], v[64:67], v[60:63]
	s_waitcnt lgkmcnt(5)
	v_mfma_f32_16x16x32_bf16 v[60:63], v[48:51], v[68:71], v[60:63]
	s_waitcnt lgkmcnt(4)
	v_mfma_f32_16x16x32_bf16 v[158:161], v[154:157], v[72:75], v[60:63]
	s_waitcnt lgkmcnt(3)
	v_mfma_f32_16x16x32_bf16 v[60:63], v[32:35], v[76:79], 0
	ds_read_b128 v[64:67], v141 offset:8704
	ds_read_b128 v[68:71], v141 offset:8768
	ds_read_b128 v[72:75], v141 offset:8832
	ds_read_b128 v[76:79], v141 offset:8896
	s_waitcnt lgkmcnt(6)
	v_mfma_f32_16x16x32_bf16 v[60:63], v[36:39], v[162:165], v[60:63]
	s_waitcnt lgkmcnt(5)
	v_mfma_f32_16x16x32_bf16 v[60:63], v[48:51], v[166:169], v[60:63]
	ds_read_b128 v[162:165], v141 offset:13056
	ds_read_b128 v[166:169], v141 offset:13120
	ds_read_b128 v[174:177], v141 offset:13184
	ds_read_b128 v[178:181], v141 offset:13248
	s_waitcnt lgkmcnt(8)
	v_mfma_f32_16x16x32_bf16 v[170:173], v[154:157], v[170:173], v[60:63]
	s_waitcnt lgkmcnt(7)
	v_mfma_f32_16x16x32_bf16 v[60:63], v[32:35], v[64:67], 0
	v_cndmask_b32_e64 v52, v52, 0, s[36:37]
	v_cndmask_b32_e64 v53, 0, v53, s[38:39]
	v_cndmask_b32_e64 v65, v54, 0, s[40:41]
	v_cndmask_b32_e64 v66, v55, 0, s[42:43]
	v_cvt_pk_bf16_f32 v64, v52, v53
	s_waitcnt lgkmcnt(6)
	v_mfma_f32_16x16x32_bf16 v[52:55], v[36:39], v[68:71], v[60:63]
	v_cndmask_b32_e64 v56, v56, 0, s[44:45]
	v_cndmask_b32_e64 v57, 0, v57, s[46:47]
	v_cndmask_b32_e64 v58, v58, 0, s[48:49]
	s_waitcnt lgkmcnt(3)
	v_mfma_f32_16x16x32_bf16 v[32:35], v[32:35], v[162:165], 0
	v_cvt_pk_bf16_f32 v65, v65, v66
	v_add_u32_e32 v60, v119, v118
	ds_write_b64 v60, v[64:65]
	v_mfma_f32_16x16x32_bf16 v[52:55], v[48:51], v[72:75], v[52:55]
	s_waitcnt lgkmcnt(3)
	v_mfma_f32_16x16x32_bf16 v[34:37], v[36:39], v[166:169], v[32:35]
	v_mfma_f32_16x16x32_bf16 v[182:185], v[154:157], v[76:79], v[52:55]
	s_nop 4
	v_cndmask_b32_e64 v53, v59, 0, s[50:51]
	v_cvt_pk_bf16_f32 v52, v56, v57
	v_cvt_pk_bf16_f32 v53, v58, v53
	v_add_u32_e32 v54, v120, v134
	ds_write_b64 v142, v[52:53]
	s_waitcnt lgkmcnt(0)
	s_barrier
	ds_read_b64_tr_b16 v[32:33], v144 offset:34816
	ds_read_b128 v[162:165], v143 offset:64
	v_mfma_f32_16x16x32_bf16 v[166:169], v[48:51], v[174:177], v[34:37]
	s_nop 2
	ds_read_b64_tr_b16 v[34:35], v144 offset:35904
	ds_read_b64_tr_b16 v[36:37], v144 offset:43520
	ds_read_b64_tr_b16 v[38:39], v144 offset:44608
	ds_read_b64_tr_b16 v[174:175], v54 offset:52224
	ds_read_b64_tr_b16 v[186:187], v54 offset:52256
	ds_read_b64_tr_b16 v[190:191], v54 offset:52288
	ds_read_b64_tr_b16 v[194:195], v54 offset:52320
	ds_read_b64_tr_b16 v[72:73], v54 offset:52352
	ds_read_b64_tr_b16 v[188:189], v54 offset:53344
	ds_read_b64_tr_b16 v[192:193], v54 offset:53376
	ds_read_b64_tr_b16 v[196:197], v54 offset:53408
	ds_read_b64_tr_b16 v[74:75], v54 offset:53440
	ds_read_b64_tr_b16 v[198:199], v54 offset:60960
	ds_read_b64_tr_b16 v[202:203], v54 offset:60992
	ds_read_b64_tr_b16 v[206:207], v54 offset:61024
	ds_read_b64_tr_b16 v[76:77], v54 offset:61056
	ds_read_b64_tr_b16 v[200:201], v54 offset:62048
	ds_read_b64_tr_b16 v[204:205], v54 offset:62080
	ds_read_b64_tr_b16 v[208:209], v54 offset:62112
	ds_read_b64_tr_b16 v[78:79], v54 offset:62144
	ds_read_b64_tr_b16 v[176:177], v54 offset:53312
	ds_read_b64_tr_b16 v[64:65], v54 offset:52384
	ds_read_b64_tr_b16 v[56:57], v54 offset:52416
	ds_read_b64_tr_b16 v[48:49], v54 offset:52448
	ds_read_b64_tr_b16 v[210:211], v54 offset:60928
	ds_read_b64_tr_b16 v[66:67], v54 offset:53472
	ds_read_b64_tr_b16 v[58:59], v54 offset:53504
	ds_read_b64_tr_b16 v[50:51], v54 offset:53536
	ds_read_b64_tr_b16 v[212:213], v54 offset:62016
	ds_read_b64_tr_b16 v[214:215], v54 offset:61088
	ds_read_b64_tr_b16 v[68:69], v54 offset:61120
	ds_read_b64_tr_b16 v[52:53], v54 offset:61152
	ds_read_b64_tr_b16 v[216:217], v54 offset:62176
	ds_read_b64_tr_b16 v[70:71], v54 offset:62208
	ds_read_b64_tr_b16 v[54:55], v54 offset:62240
	ds_read_b128 v[218:221], v143
	ds_read_b128 v[60:63], v121
	v_mfma_f32_16x16x32_bf16 v[154:157], v[154:157], v[178:181], v[166:169]
	s_waitcnt lgkmcnt(14)
; __device__ __forceinline__ unsigned pk2(float lo, float hi) { const f32x2 v = (f32x2){lo, hi}; const bf16x2_t b = __builtin_convertvector(v, bf16x2_t); return __builtin_bit_cast(unsigned, b); }
; __device__ __forceinline__ u32x4 pack8(const float* f) { u32x4 w; w.x = pk2(f[0], f[1]); w.y = pk2(f[2], f[3]); w.z = pk2(f[4], f[5]); w.w = pk2(f[6], f[7]); return w; }
; __device__ __forceinline__ void hgrn_phase(const Args& A, unsigned char* smem, const bool dry) {
;     ...
;             if (bt + 1 < 64) { HG_ISSUE(bt + 1); }
;     ...
;                 __builtin_amdgcn_sched_barrier(0);
; #pragma unroll
;                 for (int vv = 0; vv < 4; ++vv) { const int vt = 4 * hh + vv; f32x4 acc = yst[vv];
; #pragma unroll
;                     for (int ks = 0; ks < 2; ++ks) acc = __builtin_amdgcn_mfma_f32_16x16x32_bf16(aa[ks], (hh ? vf[4 + vv][ks] : vf[vv][ks]), acc, 0, 0, 0);
; #pragma unroll
;                     for (int r = 0; r < 4; ++r) yb[(16 * it + 4 * q4 + r) * 128 + 16 * vt + r16] = acc[r]; }
; #pragma unroll
;                 for (int vt = 0; vt < 8; ++vt) { Sacc[vt] = Sacc[vt] * dec;
; #pragma unroll
;                     for (int ks = 0; ks < 2; ++ks) Sacc[vt] = __builtin_amdgcn_mfma_f32_16x16x32_bf16(af[ks], vf[vt][ks], Sacc[vt], 0, 0, 0);
;                     u32x2 w; w.x = pk2(Sacc[vt][0], Sacc[vt][1]); w.y = pk2(Sacc[vt][2], Sacc[vt][3]);
;                     *(u32x2*)(Sb + (16 * vt + r16) * 136 + 16 * wave + 4 * q4) = w; }
;             }
;             __syncthreads();
;             { const int t = dir ? (SEQ - 1 - (bt * 64 + si)) : (bt * 64 + si); u16* dst = proj + (size_t)(b * SEQ + t) * PLD + 1024 + dir * 1024 + 128 * h + c16;
;                 float f[16];
; #pragma unroll
;                 for (int j = 0; j < 16; ++j) f[j] = yb[si * 128 + c16 + j];
;                 if (!dry) { *(u32x4*)dst = pack8(f); *(u32x4*)(dst + 8) = pack8(f + 8); } }
	s_nop 1
	v_cndmask_b32_e64 v169, v75, v177, s[2:3]
	v_cndmask_b32_e64 v168, v74, v176, s[2:3]
	v_cndmask_b32_e64 v167, v73, v175, s[2:3]
	v_cndmask_b32_e64 v166, v72, v174, s[2:3]
	s_waitcnt lgkmcnt(3)
	v_cndmask_b32_e64 v181, v71, v205, s[2:3]
	v_cndmask_b32_e64 v180, v70, v204, s[2:3]
	s_waitcnt lgkmcnt(1)
	v_mfma_f32_16x16x32_bf16 v[158:161], v[218:221], v[166:169], v[158:161]
	v_cndmask_b32_e64 v169, v79, v213, s[2:3]
	v_cndmask_b32_e64 v168, v78, v212, s[2:3]
	v_cndmask_b32_e64 v167, v77, v211, s[2:3]
	v_cndmask_b32_e64 v166, v76, v210, s[2:3]
	v_cndmask_b32_e64 v179, v69, v203, s[2:3]
	v_cndmask_b32_e64 v178, v68, v202, s[2:3]
	v_mfma_f32_16x16x32_bf16 v[158:161], v[162:165], v[166:169], v[158:161]
	v_cndmask_b32_e64 v169, v67, v189, s[2:3]
	v_cndmask_b32_e64 v168, v66, v188, s[2:3]
	v_cndmask_b32_e64 v167, v65, v187, s[2:3]
	v_cndmask_b32_e64 v166, v64, v186, s[2:3]
	s_waitcnt lgkmcnt(0)
	v_pk_mul_f32 v[26:27], v[26:27], v[62:63]
	v_pk_mul_f32 v[24:25], v[24:25], v[60:61]
	v_mfma_f32_16x16x32_bf16 v[166:169], v[218:221], v[166:169], v[170:173]
	v_mul_f32_e64 v2, v2, v62
	v_mul_f32_e64 v3, v3, v63
	v_pk_mul_f32 v[0:1], v[0:1], v[60:61]
	v_pk_mul_f32 v[10:11], v[10:11], v[62:63]
	v_cndmask_b32_e64 v173, v217, v201, s[2:3]
	v_cndmask_b32_e64 v172, v216, v200, s[2:3]
	v_cndmask_b32_e64 v171, v215, v199, s[2:3]
	v_cndmask_b32_e64 v170, v214, v198, s[2:3]
	v_pk_mul_f32 v[8:9], v[8:9], v[60:61]
	v_mfma_f32_16x16x32_bf16 v[24:27], v[32:35], v[56:59], v[24:27]
	v_mul_f32_e64 v30, v30, v62
	v_mul_f32_e64 v31, v31, v63
	v_pk_mul_f32 v[28:29], v[28:29], v[60:61]
	v_pk_mul_f32 v[6:7], v[6:7], v[62:63]
	v_mfma_f32_16x16x32_bf16 v[166:169], v[162:165], v[170:173], v[166:169]
	v_cndmask_b32_e64 v173, v59, v193, s[2:3]
	v_cndmask_b32_e64 v172, v58, v192, s[2:3]
	v_cndmask_b32_e64 v171, v57, v191, s[2:3]
	v_cndmask_b32_e64 v170, v56, v190, s[2:3]
	v_mfma_f32_16x16x32_bf16 v[0:3], v[32:35], v[174:177], v[0:3]
	v_mul_f32_e64 v4, v4, v60
	v_mul_f32_e64 v5, v5, v61
	v_pk_mul_f32 v[14:15], v[14:15], v[62:63]
	v_pk_mul_f32 v[12:13], v[12:13], v[60:61]
	v_mfma_f32_16x16x32_bf16 v[170:173], v[218:221], v[170:173], v[182:185]
	v_mul_f32_e64 v18, v18, v62
	v_mul_f32_e64 v19, v19, v63
	v_pk_mul_f32 v[16:17], v[16:17], v[60:61]
	v_pk_mul_f32 v[22:23], v[22:23], v[62:63]
	v_mfma_f32_16x16x32_bf16 v[170:173], v[162:165], v[178:181], v[170:173]
	v_cndmask_b32_e64 v181, v51, v197, s[2:3]
	v_cndmask_b32_e64 v180, v50, v196, s[2:3]
	v_cndmask_b32_e64 v179, v49, v195, s[2:3]
	v_cndmask_b32_e64 v178, v48, v194, s[2:3]
	v_mfma_f32_16x16x32_bf16 v[8:11], v[32:35], v[190:193], v[8:11]
	v_mul_f32_e64 v20, v20, v60
	v_mul_f32_e64 v21, v21, v61
	v_add_u32_e32 v150, 0x400, v145
	ds_write2_b32 v145, v158, v166 offset1:16
	ds_write2_b32 v145, v159, v167 offset0:128 offset1:144
	v_mfma_f32_16x16x32_bf16 v[154:157], v[218:221], v[178:181], v[154:157]
	v_cndmask_b32_e64 v181, v55, v209, s[2:3]
	v_cndmask_b32_e64 v180, v54, v208, s[2:3]
	v_cndmask_b32_e64 v179, v53, v207, s[2:3]
	v_mfma_f32_16x16x32_bf16 v[28:31], v[32:35], v[48:51], v[28:31]
	v_cndmask_b32_e64 v178, v52, v206, s[2:3]
	s_add_i32 s70, s70, 64
	s_sub_i32 s69, s69, 64
	v_mfma_f32_16x16x32_bf16 v[4:7], v[32:35], v[186:189], v[4:7]
	s_cmpk_eq_i32 s70, 0x1000
	v_mfma_f32_16x16x32_bf16 v[12:15], v[32:35], v[194:197], v[12:15]
	v_mfma_f32_16x16x32_bf16 v[16:19], v[32:35], v[72:75], v[16:19]
	v_mfma_f32_16x16x32_bf16 v[20:23], v[32:35], v[64:67], v[20:23]
	v_mfma_f32_16x16x32_bf16 v[24:27], v[36:39], v[68:71], v[24:27]
	v_mfma_f32_16x16x32_bf16 v[154:157], v[162:165], v[178:181], v[154:157]
	ds_write2_b32 v150, v160, v168 offset1:16
	ds_write2_b32 v150, v161, v169 offset0:128 offset1:144
	s_nop 5
	ds_write2_b32 v145, v170, v154 offset0:32 offset1:48
	v_cvt_pk_bf16_f32 v32, v24, v25
	v_mfma_f32_16x16x32_bf16 v[0:3], v[36:39], v[210:213], v[0:3]
	v_cvt_pk_bf16_f32 v33, v26, v27
	ds_write2_b32 v145, v171, v155 offset0:160 offset1:176
	ds_write2_b32 v150, v172, v156 offset0:32 offset1:48
	ds_write2_b32 v150, v173, v157 offset0:160 offset1:176
	v_mfma_f32_16x16x32_bf16 v[8:11], v[36:39], v[202:205], v[8:11]
	s_nop 2
	v_cvt_pk_bf16_f32 v150, v0, v1
	v_cvt_pk_bf16_f32 v151, v2, v3
	ds_write_b64 v146, v[32:33] offset:26112
	v_mfma_f32_16x16x32_bf16 v[28:31], v[36:39], v[52:55], v[28:31]
	ds_write_b64 v146, v[150:151]
	v_cvt_pk_bf16_f32 v72, v8, v9
	v_cvt_pk_bf16_f32 v73, v10, v11
	v_mfma_f32_16x16x32_bf16 v[4:7], v[36:39], v[198:201], v[4:7]
	ds_write_b64 v146, v[72:73] offset:8704
	s_nop 2
	v_cvt_pk_bf16_f32 v32, v28, v29
	v_cvt_pk_bf16_f32 v33, v30, v31
	v_mfma_f32_16x16x32_bf16 v[12:15], v[36:39], v[206:209], v[12:15]
	ds_write_b64 v146, v[32:33] offset:30464
	v_cvt_pk_bf16_f32 v150, v4, v5
	v_cvt_pk_bf16_f32 v151, v6, v7
	v_mfma_f32_16x16x32_bf16 v[16:19], v[36:39], v[76:79], v[16:19]
	v_cndmask_b32_e64 v32, v148, v149, s[52:53]
	s_nop 2
	v_cvt_pk_bf16_f32 v72, v12, v13
	v_cvt_pk_bf16_f32 v73, v14, v15
	v_mfma_f32_16x16x32_bf16 v[20:23], v[36:39], v[214:217], v[20:23]
	ds_write_b64 v146, v[150:151] offset:4352
	v_cvt_pk_bf16_f32 v64, v16, v17
	v_cvt_pk_bf16_f32 v65, v18, v19
	ds_write_b64 v146, v[72:73] offset:13056
	ds_write_b64 v146, v[64:65] offset:17408
	s_nop 2
	v_cvt_pk_bf16_f32 v56, v20, v21
	v_cvt_pk_bf16_f32 v57, v22, v23
	ds_write_b64 v146, v[56:57] offset:21760
	s_waitcnt lgkmcnt(0)
	s_barrier
	v_add_u32_e32 v56, s68, v32
	ds_read_b128 v[32:35], v147
	ds_read_b128 v[36:39], v147 offset:16
	ds_read_b128 v[48:51], v147 offset:32
	ds_read_b128 v[52:55], v147 offset:48
	v_mad_i64_i32 v[56:57], s[64:65], v56, s84, v[94:95]
	s_waitcnt lgkmcnt(3)
	v_cvt_pk_bf16_f32 v32, v32, v33
	v_cvt_pk_bf16_f32 v33, v34, v35
	s_waitcnt lgkmcnt(2)
	v_cvt_pk_bf16_f32 v34, v36, v37
	v_cvt_pk_bf16_f32 v35, v38, v39
	global_store_dwordx4 v[56:57], v[32:35], off offset:2048
	s_waitcnt vmcnt(1)
	v_mov_b64_e32 v[36:37], v[40:41]
	v_mov_b64_e32 v[38:39], v[42:43]
	s_waitcnt lgkmcnt(1)
	v_cvt_pk_bf16_f32 v32, v48, v49
	v_cvt_pk_bf16_f32 v33, v50, v51
	s_waitcnt lgkmcnt(0)
	v_cvt_pk_bf16_f32 v34, v52, v53
	v_cvt_pk_bf16_f32 v35, v54, v55
	global_store_dwordx4 v[56:57], v[32:35], off offset:2064
	v_mov_b64_e32 v[54:55], v[102:103]
	v_mov_b64_e32 v[52:53], v[100:101]
	v_mov_b64_e32 v[32:33], v[44:45]
	v_mov_b64_e32 v[48:49], v[96:97]
	v_mov_b64_e32 v[50:51], v[98:99]
	v_mov_b64_e32 v[56:57], v[104:105]
	v_mov_b64_e32 v[34:35], v[46:47]
	v_mov_b64_e32 v[62:63], v[110:111]
	v_mov_b64_e32 v[60:61], v[108:109]
	v_mov_b64_e32 v[58:59], v[106:107]
	s_cbranch_scc1 .LBB0_980
